# S5 full-pass loop software-pipelined: C-projection + GELU epilogue of chunk i-1 deferred into the LDS turnaround of chunk i
# speedup vs baseline: 1.0094x; 1.0094x over previous
.LBB0_1010:
	s_or_b64 exec, exec, s[14:15]
	v_mfma_f32_16x16x32_bf16 v[90:93], v[80:83], v[4:7], 0
	s_nop 7
	ds_write_b32 v157, v90
	ds_write_b32 v162, v91
	ds_write_b32 v157, v92 offset:1056
	ds_write_b32 v157, v93 offset:1584
	v_mfma_f32_16x16x32_bf16 v[90:93], v[80:83], v[8:11], 0
	s_nop 7
	ds_write_b32 v157, v90 offset:64
	ds_write_b32 v162, v91 offset:64
	ds_write_b32 v157, v92 offset:1120
	ds_write_b32 v157, v93 offset:1648
	v_mfma_f32_16x16x32_bf16 v[90:93], v[80:83], v[12:15], 0
	s_nop 7
	ds_write_b32 v157, v90 offset:128
	ds_write_b32 v162, v91 offset:128
	ds_write_b32 v157, v92 offset:1184
	ds_write_b32 v157, v93 offset:1712
	v_mfma_f32_16x16x32_bf16 v[90:93], v[80:83], v[16:19], 0
	s_nop 7
	ds_write_b32 v158, v90
	ds_write_b32 v163, v91
	ds_write2_b32 v94, v92, v93 offset0:8 offset1:140
	v_mfma_f32_16x16x32_bf16 v[90:93], v[80:83], v[20:23], 0
	s_nop 7
	ds_write_b32 v157, v90 offset:256
	ds_write_b32 v162, v91 offset:256
	ds_write_b32 v157, v92 offset:1312
	ds_write_b32 v157, v93 offset:1840
	v_mfma_f32_16x16x32_bf16 v[90:93], v[80:83], v[24:27], 0
	s_nop 7
	ds_write_b32 v157, v90 offset:320
	ds_write_b32 v162, v91 offset:320
	ds_write_b32 v157, v92 offset:1376
	ds_write_b32 v157, v93 offset:1904
	v_mfma_f32_16x16x32_bf16 v[90:93], v[80:83], v[28:31], 0
	s_nop 7
	ds_write_b32 v157, v90 offset:384
	ds_write_b32 v162, v91 offset:384
	ds_write_b32 v157, v92 offset:1440
	ds_write_b32 v157, v93 offset:1968
	v_mfma_f32_16x16x32_bf16 v[90:93], v[80:83], v[32:35], 0
	s_nop 7
	ds_write_b32 v159, v90
	ds_write_b32 v164, v91
	ds_write2_b32 v95, v92, v93 offset0:8 offset1:140
	s_and_saveexec_b64 s[14:15], s[4:5]
	ds_write_b128 v160, v[80:83] offset:12800
	s_or_b64 exec, exec, s[14:15]
	v_mul_f32_e32 v2, v59, v85
	v_mul_f32_e32 v66, v50, v84
	v_pk_fma_f32 v[2:3], v[58:59], v[84:85], v[2:3] op_sel_hi:[1,1,0] neg_lo:[0,0,1] neg_hi:[0,0,1]
	v_pk_fma_f32 v[66:67], v[50:51], v[84:85], v[66:67] op_sel_hi:[1,1,0]
	s_cmp_eq_u32 s16, 0
	s_cbranch_scc1 .Ls5_first
	ds_read_b128 v[188:191], v161 offset:8448
	ds_read_b128 v[192:195], v161 offset:8512
	ds_read_b128 v[196:199], v161 offset:8576
	ds_read_b128 v[208:211], v161 offset:8640
	ds_read2_b64 v[80:83], v173 offset1:66
	ds_read2_b64 v[90:93], v173 offset0:132 offset1:198
	ds_read2_b64 v[100:103], v96 offset0:8 offset1:74
	ds_read2_b64 v[104:107], v96 offset0:140 offset1:206
	ds_read2_b64 v[108:111], v97 offset0:16 offset1:82
	ds_read2_b64 v[112:115], v97 offset0:148 offset1:214
	ds_read2_b64 v[174:177], v98 offset0:24 offset1:90
	ds_read2_b64 v[178:181], v98 offset0:156 offset1:222
	s_waitcnt lgkmcnt(11)
	v_mfma_f32_16x16x32_bf16 v[188:191], v[188:191], v[60:63], 0
	s_waitcnt lgkmcnt(10)
	v_mfma_f32_16x16x32_bf16 v[188:191], v[192:195], v[52:55], v[188:191]
	s_waitcnt lgkmcnt(9)
	v_mfma_f32_16x16x32_bf16 v[188:191], v[196:199], v[44:47], v[188:191]
	s_waitcnt lgkmcnt(8)
	v_mfma_f32_16x16x32_bf16 v[188:191], v[208:211], v[36:39], v[188:191]
	v_lshlrev_b32_e32 v200, 16, v200
	v_lshlrev_b32_e32 v202, 16, v202
	s_nop 7
	v_fma_f32 v200, v135, v200, v188
	v_mul_f32_e32 v203, 0x3d372713, v200
	v_mul_f32_e32 v203, v200, v203
	v_fma_f32 v203, v200, v203, v200
	v_mul_f32_e32 v203, 0xbfcc422a, v203
	v_mul_f32_e32 v203, 0x3fb8aa3b, v203
	v_exp_f32_e32 v203, v203
	s_nop 0
	v_add_f32_e32 v203, 1.0, v203
	v_div_scale_f32 v205, s[14:15], v203, v203, v200
	v_rcp_f32_e32 v188, v205
	s_nop 0
	v_fma_f32 v206, -v205, v188, 1.0
	v_fmac_f32_e32 v188, v206, v188
	v_div_scale_f32 v206, vcc, v200, v203, v200
	v_mul_f32_e32 v207, v206, v188
	v_fma_f32 v192, -v205, v207, v206
	v_fmac_f32_e32 v207, v192, v188
	v_fma_f32 v205, -v205, v207, v206
	v_div_fmas_f32 v205, v205, v188, v207
	v_div_fixup_f32 v200, v205, v203, v200
	v_fma_f32 v205, v135, v202, v189
	v_mul_f32_e32 v202, 0x3d372713, v205
	v_mul_f32_e32 v202, v205, v202
	v_fma_f32 v202, v205, v202, v205
	v_mul_f32_e32 v202, 0xbfcc422a, v202
	v_mul_f32_e32 v202, 0x3fb8aa3b, v202
	v_exp_f32_e32 v188, v202
	v_add_u32_e32 v189, s17, v64
	v_add_u32_e32 v202, 0, v189
	v_ashrrev_i32_e32 v203, 31, v202
	v_add_f32_e32 v188, 1.0, v188
	v_div_scale_f32 v206, s[14:15], v188, v188, v205
	v_rcp_f32_e32 v207, v206
	v_lshlrev_b64 v[202:203], 11, v[202:203]
	v_cvt_pk_bf16_f32 v200, v200, s0
	v_lshl_add_u64 v[202:203], v[48:49], 0, v[202:203]
	global_store_short v[202:203], v200, off
	v_fma_f32 v200, -v206, v207, 1.0
	v_fmac_f32_e32 v207, v200, v207
	v_div_scale_f32 v200, vcc, v205, v188, v205
	v_mul_f32_e32 v202, v200, v207
	v_fma_f32 v203, -v206, v202, v200
	v_fmac_f32_e32 v202, v203, v207
	v_fma_f32 v200, -v206, v202, v200
	v_div_fmas_f32 v200, v200, v207, v202
	v_lshlrev_b32_e32 v202, 16, v201
	v_fma_f32 v201, v135, v202, v190
	v_mul_f32_e32 v202, 0x3d372713, v201
	v_mul_f32_e32 v202, v201, v202
	v_fma_f32 v202, v201, v202, v201
	v_mul_f32_e32 v202, 0xbfcc422a, v202
	v_mul_f32_e32 v202, 0x3fb8aa3b, v202
	v_div_fixup_f32 v200, v200, v188, v205
	v_exp_f32_e32 v205, v202
	v_add_u32_e32 v202, 1, v189
	v_ashrrev_i32_e32 v203, 31, v202
	v_lshlrev_b64 v[202:203], 11, v[202:203]
	v_add_f32_e32 v205, 1.0, v205
	v_div_scale_f32 v188, s[14:15], v205, v205, v201
	v_rcp_f32_e32 v190, v188
	v_cvt_pk_bf16_f32 v200, v200, s0
	v_lshl_add_u64 v[202:203], v[48:49], 0, v[202:203]
	global_store_short v[202:203], v200, off
	v_fma_f32 v200, -v188, v190, 1.0
	v_fmac_f32_e32 v190, v200, v190
	v_div_scale_f32 v200, vcc, v201, v205, v201
	v_mul_f32_e32 v202, v200, v190
	v_fma_f32 v203, -v188, v202, v200
	v_fmac_f32_e32 v202, v203, v190
	v_fma_f32 v200, -v188, v202, v200
	v_div_fmas_f32 v200, v200, v190, v202
	v_lshlrev_b32_e32 v202, 16, v204
	v_fmac_f32_e32 v191, v135, v202
	v_mul_f32_e32 v202, 0x3d372713, v191
	v_mul_f32_e32 v202, v191, v202
	v_fma_f32 v202, v191, v202, v191
	v_mul_f32_e32 v202, 0xbfcc422a, v202
	v_mul_f32_e32 v202, 0x3fb8aa3b, v202
	v_div_fixup_f32 v200, v200, v205, v201
	v_exp_f32_e32 v201, v202
	v_add_u32_e32 v202, 2, v189
	v_ashrrev_i32_e32 v203, 31, v202
	v_lshlrev_b64 v[202:203], 11, v[202:203]
	v_add_f32_e32 v201, 1.0, v201
	v_div_scale_f32 v204, s[14:15], v201, v201, v191
	v_rcp_f32_e32 v205, v204
	v_cvt_pk_bf16_f32 v200, v200, s0
	v_lshl_add_u64 v[202:203], v[48:49], 0, v[202:203]
	global_store_short v[202:203], v200, off
	v_fma_f32 v200, -v204, v205, 1.0
	v_fmac_f32_e32 v205, v200, v205
	v_div_scale_f32 v200, vcc, v191, v201, v191
	v_mul_f32_e32 v202, v200, v205
	v_fma_f32 v203, -v204, v202, v200
	v_fmac_f32_e32 v202, v203, v205
	v_fma_f32 v200, -v204, v202, v200
	v_div_fmas_f32 v200, v200, v205, v202
	v_add_u32_e32 v202, 3, v189
	v_ashrrev_i32_e32 v203, 31, v202
	v_div_fixup_f32 v200, v200, v201, v191
	v_lshlrev_b64 v[202:203], 11, v[202:203]
	v_cvt_pk_bf16_f32 v200, v200, s0
	v_lshl_add_u64 v[202:203], v[48:49], 0, v[202:203]
	global_store_short v[202:203], v200, off
	s_branch .Ls5_scan
.Ls5_first:
	ds_read2_b64 v[80:83], v173 offset1:66
	ds_read2_b64 v[90:93], v173 offset0:132 offset1:198
	ds_read2_b64 v[100:103], v96 offset0:8 offset1:74
	ds_read2_b64 v[104:107], v96 offset0:140 offset1:206
	ds_read2_b64 v[108:111], v97 offset0:16 offset1:82
	ds_read2_b64 v[112:115], v97 offset0:148 offset1:214
	ds_read2_b64 v[174:177], v98 offset0:24 offset1:90
	ds_read2_b64 v[178:181], v98 offset0:156 offset1:222
	s_waitcnt vmcnt(0)
.Ls5_scan:
	v_mov_b32_e32 v3, v67
	s_waitcnt lgkmcnt(7)
	v_pk_add_f32 v[2:3], v[2:3], v[80:81]
	s_cmpk_lt_u32 s16, 0x1f0
	v_mul_f32_e32 v66, v59, v3
	v_mul_f32_e32 v80, v50, v2
	v_cvt_pk_bf16_f32 v1, v2, v3
	v_pk_fma_f32 v[66:67], v[58:59], v[2:3], v[66:67] op_sel_hi:[1,1,0] neg_lo:[0,0,1] neg_hi:[0,0,1]
	v_pk_fma_f32 v[2:3], v[50:51], v[2:3], v[80:81] op_sel_hi:[1,1,0]
	v_lshl_add_u64 v[88:89], v[88:89], 0, s[12:13]
	v_mov_b32_e32 v67, v3
	v_pk_add_f32 v[2:3], v[82:83], v[66:67]
	v_add_u32_e32 v66, 0x2000, v165
	v_cvt_pk_bf16_f32 v65, v2, v3
	ds_write2_b32 v66, v1, v65 offset0:64 offset1:132
	v_mul_f32_e32 v66, v59, v3
	v_mul_f32_e32 v80, v50, v2
	v_pk_fma_f32 v[66:67], v[58:59], v[2:3], v[66:67] op_sel_hi:[1,1,0] neg_lo:[0,0,1] neg_hi:[0,0,1]
	v_pk_fma_f32 v[2:3], v[50:51], v[2:3], v[80:81] op_sel_hi:[1,1,0]
	s_nop 0
	v_mov_b32_e32 v67, v3
	s_waitcnt lgkmcnt(7)
	v_pk_add_f32 v[2:3], v[90:91], v[66:67]
	s_nop 0
	v_mul_f32_e32 v66, v59, v3
	v_mul_f32_e32 v80, v50, v2
	v_cvt_pk_bf16_f32 v1, v2, v3
	v_pk_fma_f32 v[66:67], v[58:59], v[2:3], v[66:67] op_sel_hi:[1,1,0] neg_lo:[0,0,1] neg_hi:[0,0,1]
	v_pk_fma_f32 v[2:3], v[50:51], v[2:3], v[80:81] op_sel_hi:[1,1,0]
	s_nop 0
	v_mov_b32_e32 v67, v3
	v_pk_add_f32 v[2:3], v[92:93], v[66:67]
	v_add_u32_e32 v66, 0x2200, v165
	v_cvt_pk_bf16_f32 v65, v2, v3
	ds_write2_b32 v66, v1, v65 offset0:72 offset1:140
	v_mul_f32_e32 v66, v59, v3
	v_mul_f32_e32 v80, v50, v2
	v_pk_fma_f32 v[66:67], v[58:59], v[2:3], v[66:67] op_sel_hi:[1,1,0] neg_lo:[0,0,1] neg_hi:[0,0,1]
	v_pk_fma_f32 v[2:3], v[50:51], v[2:3], v[80:81] op_sel_hi:[1,1,0]
	s_nop 0
	v_mov_b32_e32 v67, v3
	s_waitcnt lgkmcnt(7)
	v_pk_add_f32 v[2:3], v[100:101], v[66:67]
	s_nop 0
	v_mul_f32_e32 v66, v59, v3
	v_mul_f32_e32 v80, v50, v2
	v_cvt_pk_bf16_f32 v1, v2, v3
	v_pk_fma_f32 v[66:67], v[58:59], v[2:3], v[66:67] op_sel_hi:[1,1,0] neg_lo:[0,0,1] neg_hi:[0,0,1]
	v_pk_fma_f32 v[2:3], v[50:51], v[2:3], v[80:81] op_sel_hi:[1,1,0]
	s_nop 0
	v_mov_b32_e32 v67, v3
	v_pk_add_f32 v[2:3], v[102:103], v[66:67]
	v_add_u32_e32 v66, 0x2400, v165
	v_cvt_pk_bf16_f32 v65, v2, v3
	ds_write2_b32 v66, v1, v65 offset0:80 offset1:148
	v_mul_f32_e32 v66, v59, v3
	v_mul_f32_e32 v80, v50, v2
	v_pk_fma_f32 v[66:67], v[58:59], v[2:3], v[66:67] op_sel_hi:[1,1,0] neg_lo:[0,0,1] neg_hi:[0,0,1]
	v_pk_fma_f32 v[2:3], v[50:51], v[2:3], v[80:81] op_sel_hi:[1,1,0]
	s_nop 0
	v_mov_b32_e32 v67, v3
	s_waitcnt lgkmcnt(7)
	v_pk_add_f32 v[2:3], v[104:105], v[66:67]
	s_nop 0
	v_mul_f32_e32 v66, v59, v3
	v_mul_f32_e32 v80, v50, v2
	v_cvt_pk_bf16_f32 v1, v2, v3
	v_pk_fma_f32 v[66:67], v[58:59], v[2:3], v[66:67] op_sel_hi:[1,1,0] neg_lo:[0,0,1] neg_hi:[0,0,1]
	v_pk_fma_f32 v[2:3], v[50:51], v[2:3], v[80:81] op_sel_hi:[1,1,0]
	s_nop 0
	v_mov_b32_e32 v67, v3
	v_pk_add_f32 v[2:3], v[106:107], v[66:67]
	v_add_u32_e32 v66, 0x2600, v165
	v_cvt_pk_bf16_f32 v65, v2, v3
	ds_write2_b32 v66, v1, v65 offset0:88 offset1:156
	v_mul_f32_e32 v66, v59, v3
	v_mul_f32_e32 v80, v50, v2
	v_pk_fma_f32 v[66:67], v[58:59], v[2:3], v[66:67] op_sel_hi:[1,1,0] neg_lo:[0,0,1] neg_hi:[0,0,1]
	v_pk_fma_f32 v[2:3], v[50:51], v[2:3], v[80:81] op_sel_hi:[1,1,0]
	s_nop 0
	v_mov_b32_e32 v67, v3
	s_waitcnt lgkmcnt(7)
	v_pk_add_f32 v[2:3], v[108:109], v[66:67]
	s_nop 0
	v_mul_f32_e32 v66, v59, v3
	v_mul_f32_e32 v80, v50, v2
	v_cvt_pk_bf16_f32 v1, v2, v3
	v_pk_fma_f32 v[66:67], v[58:59], v[2:3], v[66:67] op_sel_hi:[1,1,0] neg_lo:[0,0,1] neg_hi:[0,0,1]
	v_pk_fma_f32 v[2:3], v[50:51], v[2:3], v[80:81] op_sel_hi:[1,1,0]
	s_nop 0
	v_mov_b32_e32 v67, v3
	v_pk_add_f32 v[2:3], v[110:111], v[66:67]
	v_add_u32_e32 v66, 0x2800, v165
	v_cvt_pk_bf16_f32 v65, v2, v3
	ds_write2_b32 v66, v1, v65 offset0:96 offset1:164
	v_mul_f32_e32 v66, v59, v3
	v_mul_f32_e32 v80, v50, v2
	v_pk_fma_f32 v[66:67], v[58:59], v[2:3], v[66:67] op_sel_hi:[1,1,0] neg_lo:[0,0,1] neg_hi:[0,0,1]
	v_pk_fma_f32 v[2:3], v[50:51], v[2:3], v[80:81] op_sel_hi:[1,1,0]
	s_nop 0
	v_mov_b32_e32 v67, v3
	s_waitcnt lgkmcnt(7)
	v_pk_add_f32 v[2:3], v[112:113], v[66:67]
	s_nop 0
	v_mul_f32_e32 v66, v59, v3
	v_mul_f32_e32 v80, v50, v2
	v_cvt_pk_bf16_f32 v1, v2, v3
	v_pk_fma_f32 v[66:67], v[58:59], v[2:3], v[66:67] op_sel_hi:[1,1,0] neg_lo:[0,0,1] neg_hi:[0,0,1]
	v_pk_fma_f32 v[2:3], v[50:51], v[2:3], v[80:81] op_sel_hi:[1,1,0]
	s_nop 0
	v_mov_b32_e32 v67, v3
	v_pk_add_f32 v[2:3], v[114:115], v[66:67]
	v_add_u32_e32 v66, 0x2a00, v165
	v_cvt_pk_bf16_f32 v65, v2, v3
	ds_write2_b32 v66, v1, v65 offset0:104 offset1:172
	v_pk_mul_f32 v[66:67], v[140:141], v[2:3]
	s_nop 0
	v_pk_fma_f32 v[80:81], v[138:139], v[2:3], v[66:67] op_sel:[0,0,1] op_sel_hi:[1,1,0] neg_lo:[0,0,1] neg_hi:[0,0,1]
	v_pk_fma_f32 v[2:3], v[138:139], v[2:3], v[66:67] op_sel:[0,0,1] op_sel_hi:[1,1,0]
	s_nop 0
	v_mov_b32_e32 v81, v3
	s_waitcnt lgkmcnt(7)
	v_pk_add_f32 v[2:3], v[174:175], v[80:81]
	s_nop 0
	v_pk_mul_f32 v[66:67], v[140:141], v[2:3]
	v_cvt_pk_bf16_f32 v1, v2, v3
	v_pk_fma_f32 v[80:81], v[56:57], v[2:3], v[66:67] op_sel:[0,0,1] op_sel_hi:[1,1,0]
	v_pk_fma_f32 v[2:3], v[56:57], v[2:3], v[66:67] op_sel:[0,0,1] op_sel_hi:[1,1,0] neg_lo:[0,0,1] neg_hi:[0,0,1]
	v_add_u32_e32 v66, 0x2c00, v165
	v_mov_b32_e32 v3, v81
	v_pk_add_f32 v[2:3], v[176:177], v[2:3]
	s_nop 0
	v_cvt_pk_bf16_f32 v65, v2, v3
	ds_write2_b32 v66, v1, v65 offset0:112 offset1:180
	v_pk_mul_f32 v[66:67], v[140:141], v[2:3]
	s_nop 0
	v_pk_fma_f32 v[80:81], v[56:57], v[2:3], v[66:67] op_sel:[0,0,1] op_sel_hi:[1,1,0]
	v_pk_fma_f32 v[2:3], v[56:57], v[2:3], v[66:67] op_sel:[0,0,1] op_sel_hi:[1,1,0] neg_lo:[0,0,1] neg_hi:[0,0,1]
	s_nop 0
	v_mov_b32_e32 v3, v81
	s_waitcnt lgkmcnt(7)
	v_pk_add_f32 v[2:3], v[178:179], v[2:3]
	s_nop 0
	v_pk_mul_f32 v[66:67], v[140:141], v[2:3]
	v_cvt_pk_bf16_f32 v1, v2, v3
	v_pk_fma_f32 v[80:81], v[56:57], v[2:3], v[66:67] op_sel:[0,0,1] op_sel_hi:[1,1,0]
	v_pk_fma_f32 v[2:3], v[56:57], v[2:3], v[66:67] op_sel:[0,0,1] op_sel_hi:[1,1,0] neg_lo:[0,0,1] neg_hi:[0,0,1]
	s_nop 0
	v_mov_b32_e32 v3, v81
	v_pk_add_f32 v[84:85], v[180:181], v[2:3]
	v_add_u32_e32 v3, 0x2e00, v165
	v_cvt_pk_bf16_f32 v2, v84, v85
	ds_write2_b32 v3, v1, v2 offset0:120 offset1:188
	ds_read_u16 v200, v166 offset:12800
	ds_read_u16 v202, v167 offset:12800
	ds_read_u16 v201, v168 offset:12800
	ds_read_u16 v204, v169 offset:12800
	s_waitcnt lgkmcnt(0)
	s_cbranch_scc0 .Ls5_lastE
	s_waitcnt vmcnt(4)
	v_mov_b64_e32 v[82:83], v[70:71]
	v_mov_b64_e32 v[80:81], v[68:69]
	v_mov_b64_e32 v[68:69], v[72:73]
	v_mov_b64_e32 v[70:71], v[74:75]
	v_mov_b64_e32 v[72:73], v[76:77]
	v_mov_b64_e32 v[74:75], v[78:79]
	v_mov_b64_e32 v[78:79], v[42:43]
	s_mov_b32 s17, s16
	v_mov_b64_e32 v[76:77], v[40:41]
	s_branch .LBB0_1008
.Ls5_lastE:
	ds_read_b128 v[188:191], v161 offset:8448
	ds_read_b128 v[192:195], v161 offset:8512
	ds_read_b128 v[196:199], v161 offset:8576
	ds_read_b128 v[208:211], v161 offset:8640
	s_waitcnt lgkmcnt(3)
	v_mfma_f32_16x16x32_bf16 v[188:191], v[188:191], v[60:63], 0
	s_waitcnt lgkmcnt(2)
	v_mfma_f32_16x16x32_bf16 v[188:191], v[192:195], v[52:55], v[188:191]
	s_waitcnt lgkmcnt(1)
	v_mfma_f32_16x16x32_bf16 v[188:191], v[196:199], v[44:47], v[188:191]
	s_waitcnt lgkmcnt(0)
	v_mfma_f32_16x16x32_bf16 v[188:191], v[208:211], v[36:39], v[188:191]
	v_lshlrev_b32_e32 v200, 16, v200
	v_lshlrev_b32_e32 v202, 16, v202
	s_nop 7
	v_fma_f32 v200, v135, v200, v188
	v_mul_f32_e32 v203, 0x3d372713, v200
	v_mul_f32_e32 v203, v200, v203
	v_fma_f32 v203, v200, v203, v200
	v_mul_f32_e32 v203, 0xbfcc422a, v203
	v_mul_f32_e32 v203, 0x3fb8aa3b, v203
	v_exp_f32_e32 v203, v203
	s_nop 0
	v_add_f32_e32 v203, 1.0, v203
	v_div_scale_f32 v205, s[14:15], v203, v203, v200
	v_rcp_f32_e32 v188, v205
	s_nop 0
	v_fma_f32 v206, -v205, v188, 1.0
	v_fmac_f32_e32 v188, v206, v188
	v_div_scale_f32 v206, vcc, v200, v203, v200
	v_mul_f32_e32 v207, v206, v188
	v_fma_f32 v192, -v205, v207, v206
	v_fmac_f32_e32 v207, v192, v188
	v_fma_f32 v205, -v205, v207, v206
	v_div_fmas_f32 v205, v205, v188, v207
	v_div_fixup_f32 v200, v205, v203, v200
	v_fma_f32 v205, v135, v202, v189
	v_mul_f32_e32 v202, 0x3d372713, v205
	v_mul_f32_e32 v202, v205, v202
	v_fma_f32 v202, v205, v202, v205
	v_mul_f32_e32 v202, 0xbfcc422a, v202
	v_mul_f32_e32 v202, 0x3fb8aa3b, v202
	v_exp_f32_e32 v188, v202
	v_add_u32_e32 v189, s17, v64
	v_add_u32_e32 v202, 16, v189
	v_ashrrev_i32_e32 v203, 31, v202
	v_add_f32_e32 v188, 1.0, v188
	v_div_scale_f32 v206, s[14:15], v188, v188, v205
	v_rcp_f32_e32 v207, v206
	v_lshlrev_b64 v[202:203], 11, v[202:203]
	v_cvt_pk_bf16_f32 v200, v200, s0
	v_lshl_add_u64 v[202:203], v[48:49], 0, v[202:203]
	global_store_short v[202:203], v200, off
	v_fma_f32 v200, -v206, v207, 1.0
	v_fmac_f32_e32 v207, v200, v207
	v_div_scale_f32 v200, vcc, v205, v188, v205
	v_mul_f32_e32 v202, v200, v207
	v_fma_f32 v203, -v206, v202, v200
	v_fmac_f32_e32 v202, v203, v207
	v_fma_f32 v200, -v206, v202, v200
	v_div_fmas_f32 v200, v200, v207, v202
	v_lshlrev_b32_e32 v202, 16, v201
	v_fma_f32 v201, v135, v202, v190
	v_mul_f32_e32 v202, 0x3d372713, v201
	v_mul_f32_e32 v202, v201, v202
	v_fma_f32 v202, v201, v202, v201
	v_mul_f32_e32 v202, 0xbfcc422a, v202
	v_mul_f32_e32 v202, 0x3fb8aa3b, v202
	v_div_fixup_f32 v200, v200, v188, v205
	v_exp_f32_e32 v205, v202
	v_add_u32_e32 v202, 17, v189
	v_ashrrev_i32_e32 v203, 31, v202
	v_lshlrev_b64 v[202:203], 11, v[202:203]
	v_add_f32_e32 v205, 1.0, v205
	v_div_scale_f32 v188, s[14:15], v205, v205, v201
	v_rcp_f32_e32 v190, v188
	v_cvt_pk_bf16_f32 v200, v200, s0
	v_lshl_add_u64 v[202:203], v[48:49], 0, v[202:203]
	global_store_short v[202:203], v200, off
	v_fma_f32 v200, -v188, v190, 1.0
	v_fmac_f32_e32 v190, v200, v190
	v_div_scale_f32 v200, vcc, v201, v205, v201
	v_mul_f32_e32 v202, v200, v190
	v_fma_f32 v203, -v188, v202, v200
	v_fmac_f32_e32 v202, v203, v190
	v_fma_f32 v200, -v188, v202, v200
	v_div_fmas_f32 v200, v200, v190, v202
	v_lshlrev_b32_e32 v202, 16, v204
	v_fmac_f32_e32 v191, v135, v202
	v_mul_f32_e32 v202, 0x3d372713, v191
	v_mul_f32_e32 v202, v191, v202
	v_fma_f32 v202, v191, v202, v191
	v_mul_f32_e32 v202, 0xbfcc422a, v202
	v_mul_f32_e32 v202, 0x3fb8aa3b, v202
	v_div_fixup_f32 v200, v200, v205, v201
	v_exp_f32_e32 v201, v202
	v_add_u32_e32 v202, 18, v189
	v_ashrrev_i32_e32 v203, 31, v202
	v_lshlrev_b64 v[202:203], 11, v[202:203]
	v_add_f32_e32 v201, 1.0, v201
	v_div_scale_f32 v204, s[14:15], v201, v201, v191
	v_rcp_f32_e32 v205, v204
	v_cvt_pk_bf16_f32 v200, v200, s0
	v_lshl_add_u64 v[202:203], v[48:49], 0, v[202:203]
	global_store_short v[202:203], v200, off
	v_fma_f32 v200, -v204, v205, 1.0
	v_fmac_f32_e32 v205, v200, v205
	v_div_scale_f32 v200, vcc, v191, v201, v191
	v_mul_f32_e32 v202, v200, v205
	v_fma_f32 v203, -v204, v202, v200
	v_fmac_f32_e32 v202, v203, v205
	v_fma_f32 v200, -v204, v202, v200
	v_div_fmas_f32 v200, v200, v205, v202
	v_add_u32_e32 v202, 19, v189
	v_ashrrev_i32_e32 v203, 31, v202
	v_div_fixup_f32 v200, v200, v201, v191
	v_lshlrev_b64 v[202:203], 11, v[202:203]
	v_cvt_pk_bf16_f32 v200, v200, s0
	v_lshl_add_u64 v[202:203], v[48:49], 0, v[202:203]
	global_store_short v[202:203], v200, off
